# rows phases: the two per-row 64-lane sums by DPP row shifts/broadcasts + v_readlane instead of 12 ds_bpermute round trips per row
# speedup vs baseline: 1.0096x; 1.0096x over previous
.LBB0_542:
	s_or_b64 exec, exec, s[0:1]
	s_and_b64 vcc, exec, s[38:39]
	v_ashrrev_i32_e32 v133, 31, v132
	s_cbranch_vccnz .LBB0_551
	v_lshlrev_b32_e32 v142, 16, v72
	v_and_b32_e32 v143, 0xffff0000, v72
	v_lshlrev_b32_e32 v94, 16, v84
	v_and_b32_e32 v95, 0xffff0000, v84
	v_lshlrev_b32_e32 v92, 16, v85
	v_and_b32_e32 v93, 0xffff0000, v85
	v_lshlrev_b32_e32 v90, 16, v86
	v_and_b32_e32 v91, 0xffff0000, v86
	v_lshlrev_b32_e32 v84, 16, v87
	v_and_b32_e32 v85, 0xffff0000, v87
	v_lshlrev_b32_e32 v72, 16, v73
	v_and_b32_e32 v73, 0xffff0000, v73
	v_pk_mul_f32 v[86:87], v[142:143], v[142:143]
	v_pk_mul_f32 v[146:147], v[72:73], v[72:73]
	v_add_f32_e32 v86, v86, v87
	v_lshlrev_b32_e32 v144, 16, v74
	v_and_b32_e32 v145, 0xffff0000, v74
	v_add_f32_e32 v86, v146, v86
	v_pk_mul_f32 v[148:149], v[144:145], v[144:145]
	v_add_f32_e32 v86, v147, v86
	v_lshlrev_b32_e32 v74, 16, v75
	v_and_b32_e32 v75, 0xffff0000, v75
	v_add_f32_e32 v86, v148, v86
	v_pk_mul_f32 v[150:151], v[74:75], v[74:75]
	v_add_f32_e32 v86, v149, v86
	v_add_f32_e32 v86, v150, v86
	v_pk_mul_f32 v[152:153], v[94:95], v[94:95]
	v_add_f32_e32 v86, v151, v86
	v_add_f32_e32 v86, v152, v86
	v_pk_mul_f32 v[154:155], v[92:93], v[92:93]
	v_add_f32_e32 v86, v153, v86
	v_add_f32_e32 v86, v154, v86
	v_pk_mul_f32 v[156:157], v[90:91], v[90:91]
	v_add_f32_e32 v86, v155, v86
	v_add_f32_e32 v86, v156, v86
	v_add_u32_e32 v87, 64, v237
	v_pk_mul_f32 v[158:159], v[84:85], v[84:85]
	v_add_f32_e32 v86, v157, v86
	v_add_f32_e32 v86, v158, v86
	v_add_f32_e32 v86, v159, v86
	s_mov_b32 s0, 0xf800000
	v_readlane_b32 s4, v254, 24
	v_readlane_b32 s5, v254, 25
	s_nop 1
	v_add_f32_dpp v86, v86, v86 row_shr:1 row_mask:0xf bank_mask:0xf
	s_nop 1
	v_add_f32_dpp v86, v86, v86 row_shr:2 row_mask:0xf bank_mask:0xf
	s_nop 1
	v_add_f32_dpp v86, v86, v86 row_shr:4 row_mask:0xf bank_mask:0xf
	s_nop 1
	v_add_f32_dpp v86, v86, v86 row_shr:8 row_mask:0xf bank_mask:0xf
	s_nop 1
	v_add_f32_dpp v86, v86, v86 row_bcast:15 row_mask:0xa bank_mask:0xf
	s_nop 1
	v_add_f32_dpp v86, v86, v86 row_bcast:31 row_mask:0xc bank_mask:0xf
	s_nop 1
	v_readlane_b32 s32, v86, 63
	s_nop 1
	v_mov_b32_e32 v86, s32
	v_fmamk_f32 v86, v86, 0x3a800000, v225
	v_mul_f32_e32 v87, 0x4f800000, v86
	v_cmp_gt_f32_e32 vcc, s0, v86
	s_nop 1
	v_cndmask_b32_e32 v86, v86, v87, vcc
	v_sqrt_f32_e32 v87, v86
	s_nop 0
	v_add_u32_e32 v89, -1, v87
	v_fma_f32 v112, -v89, v87, v86
	v_cmp_ge_f32_e64 s[44:45], 0, v112
	v_add_u32_e32 v112, 1, v87
	s_nop 0
	v_cndmask_b32_e64 v89, v87, v89, s[44:45]
	v_fma_f32 v87, -v112, v87, v86
	v_cmp_lt_f32_e64 s[44:45], 0, v87
	s_nop 1
	v_cndmask_b32_e64 v87, v89, v112, s[44:45]
	v_mul_f32_e32 v89, 0x37800000, v87
	v_cndmask_b32_e32 v87, v87, v89, vcc
	v_cmp_class_f32_e32 vcc, v86, v226
	s_nop 1
	v_cndmask_b32_e32 v86, v87, v86, vcc
	v_div_scale_f32 v87, s[0:1], v86, v86, 1.0
	v_rcp_f32_e32 v89, v87
	s_mov_b64 s[0:1], -1
	v_fma_f32 v112, -v87, v89, 1.0
	v_fmac_f32_e32 v89, v112, v89
	v_div_scale_f32 v112, vcc, 1.0, v86, 1.0
	v_mul_f32_e32 v141, v112, v89
	v_fma_f32 v146, -v87, v141, v112
	v_fmac_f32_e32 v141, v146, v89
	v_fma_f32 v87, -v87, v141, v112
	v_div_fmas_f32 v87, v87, v89, v141
	v_div_fixup_f32 v86, v87, v86, 1.0
	v_pk_mul_f32 v[72:73], v[86:87], v[72:73] op_sel_hi:[0,1]
	v_pk_fma_f32 v[38:39], v[102:103], v[72:73], v[38:39]
	v_pk_mul_f32 v[72:73], v[86:87], v[144:145] op_sel_hi:[0,1]
	v_pk_fma_f32 v[32:33], v[106:107], v[72:73], v[32:33]
	v_pk_mul_f32 v[72:73], v[86:87], v[74:75] op_sel_hi:[0,1]
	v_pk_mul_f32 v[142:143], v[86:87], v[142:143] op_sel_hi:[0,1]
	v_pk_fma_f32 v[34:35], v[110:111], v[72:73], v[34:35]
	v_lshlrev_b64 v[72:73], 11, v[132:133]
	v_pk_fma_f32 v[36:37], v[98:99], v[142:143], v[36:37]
	v_lshl_add_u64 v[74:75], v[114:115], 0, v[72:73]
	s_and_b64 vcc, exec, s[4:5]
	s_cbranch_vccz .LBB0_545
	v_cvt_pk_bf16_f32 v142, v36, v37
	v_cvt_pk_bf16_f32 v143, v38, v39
	v_cvt_pk_bf16_f32 v144, v32, v33
	v_cvt_pk_bf16_f32 v145, v34, v35
	global_store_dwordx4 v[74:75], v[142:145], off
	s_mov_b64 s[0:1], 0

.LBB0_553:
	s_and_b64 vcc, exec, s[40:41]
	s_cbranch_vccnz .LBB0_526
	v_mul_f32_e32 v74, v37, v37
	v_fmac_f32_e32 v74, v36, v36
	v_fmac_f32_e32 v74, v38, v38
	v_fmac_f32_e32 v74, v39, v39
	v_fmac_f32_e32 v74, v32, v32
	v_fmac_f32_e32 v74, v33, v33
	v_fmac_f32_e32 v74, v34, v34
	v_fmac_f32_e32 v74, v35, v35
	v_fmac_f32_e32 v74, v44, v44
	v_fmac_f32_e32 v74, v45, v45
	v_fmac_f32_e32 v74, v46, v46
	v_fmac_f32_e32 v74, v47, v47
	v_fmac_f32_e32 v74, v40, v40
	v_fmac_f32_e32 v74, v41, v41
	v_pk_mul_f32 v[72:73], v[42:43], v[42:43]
	s_mov_b32 s0, 0xf800000
	v_add_f32_e32 v72, v72, v74
	v_add_f32_e32 v72, v73, v72
	v_add_u32_e32 v73, 64, v237
	s_nop 1
	v_add_f32_dpp v72, v72, v72 row_shr:1 row_mask:0xf bank_mask:0xf
	s_nop 1
	v_add_f32_dpp v72, v72, v72 row_shr:2 row_mask:0xf bank_mask:0xf
	s_nop 1
	v_add_f32_dpp v72, v72, v72 row_shr:4 row_mask:0xf bank_mask:0xf
	s_nop 1
	v_add_f32_dpp v72, v72, v72 row_shr:8 row_mask:0xf bank_mask:0xf
	s_nop 1
	v_add_f32_dpp v72, v72, v72 row_bcast:15 row_mask:0xa bank_mask:0xf
	s_nop 1
	v_add_f32_dpp v72, v72, v72 row_bcast:31 row_mask:0xc bank_mask:0xf
	s_nop 1
	v_readlane_b32 s32, v72, 63
	s_nop 1
	v_mov_b32_e32 v72, s32
	v_fmamk_f32 v72, v72, 0x3a800000, v225
	v_mul_f32_e32 v73, 0x4f800000, v72
	v_cmp_gt_f32_e32 vcc, s0, v72
	s_nop 1
	v_cndmask_b32_e32 v72, v72, v73, vcc
	v_sqrt_f32_e32 v73, v72
	s_nop 0
	v_add_u32_e32 v74, -1, v73
	v_fma_f32 v75, -v74, v73, v72
	v_cmp_ge_f32_e64 s[44:45], 0, v75
	v_add_u32_e32 v75, 1, v73
	s_nop 0
	v_cndmask_b32_e64 v74, v73, v74, s[44:45]
	v_fma_f32 v73, -v75, v73, v72
	v_cmp_lt_f32_e64 s[44:45], 0, v73
	s_nop 1
	v_cndmask_b32_e64 v73, v74, v75, s[44:45]
	v_mul_f32_e32 v74, 0x37800000, v73
	v_cndmask_b32_e32 v73, v73, v74, vcc
	v_cmp_class_f32_e32 vcc, v72, v226
	s_nop 1
	v_cndmask_b32_e32 v72, v73, v72, vcc
	v_div_scale_f32 v73, s[0:1], v72, v72, 1.0
	v_rcp_f32_e32 v74, v73
	s_nop 0
	v_fma_f32 v75, -v73, v74, 1.0
	v_fmac_f32_e32 v74, v75, v74
	v_div_scale_f32 v75, vcc, 1.0, v72, 1.0
	v_mul_f32_e32 v84, v75, v74
	v_fma_f32 v85, -v73, v84, v75
	v_fmac_f32_e32 v84, v85, v74
	v_fma_f32 v73, -v73, v84, v75
	v_div_fmas_f32 v73, v73, v74, v84
	v_div_fixup_f32 v72, v73, v72, 1.0
	v_pk_mul_f32 v[36:37], v[36:37], v[72:73] op_sel_hi:[1,0]
	v_pk_mul_f32 v[38:39], v[38:39], v[72:73] op_sel_hi:[1,0]
	v_pk_mul_f32 v[32:33], v[32:33], v[72:73] op_sel_hi:[1,0]
	v_pk_mul_f32 v[36:37], v[96:97], v[36:37]
	v_pk_mul_f32 v[38:39], v[100:101], v[38:39]
	v_pk_mul_f32 v[32:33], v[104:105], v[32:33]
	v_cvt_pk_bf16_f32 v36, v36, v37
	v_cvt_pk_bf16_f32 v37, v38, v39
	v_cvt_pk_bf16_f32 v38, v32, v33
	v_pk_mul_f32 v[32:33], v[34:35], v[72:73] op_sel_hi:[1,0]
	v_lshlrev_b64 v[74:75], 11, v[132:133]
	v_pk_mul_f32 v[32:33], v[108:109], v[32:33]
	v_pk_mul_f32 v[34:35], v[46:47], v[72:73] op_sel_hi:[1,0]
	v_cvt_pk_bf16_f32 v39, v32, v33
	v_pk_mul_f32 v[32:33], v[44:45], v[72:73] op_sel_hi:[1,0]
	v_lshl_add_u64 v[74:75], v[138:139], 0, v[74:75]
	v_pk_mul_f32 v[32:33], v[116:117], v[32:33]
	v_pk_mul_f32 v[34:35], v[120:121], v[34:35]
	global_store_dwordx4 v[74:75], v[36:39], off
	v_cvt_pk_bf16_f32 v32, v32, v33
	v_cvt_pk_bf16_f32 v33, v34, v35
	v_pk_mul_f32 v[34:35], v[40:41], v[72:73] op_sel_hi:[1,0]
	v_pk_mul_f32 v[36:37], v[42:43], v[72:73] op_sel_hi:[1,0]
	v_pk_mul_f32 v[34:35], v[124:125], v[34:35]
	v_pk_mul_f32 v[36:37], v[128:129], v[36:37]
	v_cvt_pk_bf16_f32 v34, v34, v35
	v_cvt_pk_bf16_f32 v35, v36, v37
	global_store_dwordx4 v[74:75], v[32:35], off offset:1024
	s_branch .LBB0_526
